# bundle25 + static s_setprio 1 for waves 0-3 (the other half) across the attention loop, for comparison with the waves 4-7 build
# speedup vs baseline: 1.0074x; 1.0017x over previous
.LBB0_1132:
	s_or_b64 exec, exec, s[0:1]
	s_cmpk_lt_i32 s84, 0x100
	s_cselect_b64 s[34:35], -1, 0
	s_cmpk_gt_i32 s84, 0xff
	s_waitcnt vmcnt(0) lgkmcnt(0)
	s_barrier
	s_cbranch_scc1 .LBB0_1246
	v_readfirstlane_b32 s0, v0
	s_nop 3
	s_and_b32 s0, s0, 0x3ff
	s_lshr_b32 s0, s0, 6
	s_cmp_lt_u32 s0, 4
	s_cbranch_scc0 .Lattn_prio_done
	s_setprio 1
